# selected-branch interior tile: K fragment reads all issued up front, V fragment reads issued behind the last QK MFMA (no waits on just-issued LDS reads)
# speedup vs baseline: 1.0072x; 1.0045x over previous
; #define LAS __attribute__((address_space(3)))
; template <int BR>
; DI void attn_branch(const AttnCtx& c, unsigned long long tmask, const bf16_t* kbase, size_t kpitch, const bf16_t* vbase, size_t vpitch, f32x16 (&o)[2], float& lsum) {
;     ...
;         bool mine = true;
;         if (BR == 2) mine = (c.mymask >> jc) & 1ull;
;         const bool wave_on = (BR == 2 ? (__ballot(mine) != 0ull) : true) && !c.nocompute;
;         if (wave_on) {
;             const float sbias = (BR == 2 && !mine) ? -1e30f : 0.f;
;             bool interior;
;             if (BR <= 1) interior = jc * 64 + 64 <= c.ncvmin;
;             else if (BR == 2) interior = jc * 64 + 63 <= c.tw;
;             else interior = (jc * 64 + 63 <= c.tw) && (jc * 64 > c.tw + 31 - 512);
;             if (interior) {
;                 f32x16 s0, s1;
; #pragma unroll
;                 for (int i = 0; i < 16; ++i) { s0[i] = sbias; s1[i] = sbias; }
; #pragma unroll
;                 for (int st = 0; st < 4; ++st) {
;                     const bf16x8 kf0 = *(const LAS bf16x8*)(Ks + c.qi * 72 + 16 * st + 8 * c.hi), kf1 = *(const LAS bf16x8*)(Ks + (32 + c.qi) * 72 + 16 * st + 8 * c.hi);
;                     s0 = MFMA32(kf0, c.q[st], s0); s1 = MFMA32(kf1, c.q[st], s1);
;                 }
;                 float p0[16], p1[16];
; #pragma unroll
;                 for (int i = 0; i < 16; ++i) { p0[i] = __builtin_amdgcn_exp2f(s0[i]); p1[i] = __builtin_amdgcn_exp2f(s1[i]); }
;                 {
;                     float l0 = 0.f, l1 = 0.f;
; #pragma unroll
;                     for (int i = 0; i < 16; ++i) { l0 += p0[i]; l1 += p1[i]; }
;                     lsum += l0 + l1;
;                 }
;                 if (BR == 1) {
; #pragma unroll
;                     for (int gq = 0; gq < 4; ++gq) {
;                         const int jj = jc * 16 + gq * 2 + c.hi;
;                         __hip_atomic_fetch_add(c.impw + jj, (p0[4 * gq] + p0[4 * gq + 1]) + (p0[4 * gq + 2] + p0[4 * gq + 3]), __ATOMIC_RELAXED, __HIP_MEMORY_SCOPE_WORKGROUP);
;                         __hip_atomic_fetch_add(c.impw + jj + 1, p0[4 * gq + 3], __ATOMIC_RELAXED, __HIP_MEMORY_SCOPE_WORKGROUP);
;                     }
; #pragma unroll
;                     for (int gq = 0; gq < 4; ++gq) {
;                         const int jj = jc * 16 + 8 + gq * 2 + c.hi;
.LBB0_377:
	s_waitcnt lgkmcnt(0)
	s_barrier
	v_lshrrev_b64 v[64:65], s10, v[106:107]
	v_and_b32_e32 v64, 1, v64
	v_cmp_eq_u32_e64 s[0:1], 1, v64
	v_cmp_ne_u32_e32 vcc, 0, v64
	s_cbranch_vccz .LBB0_387
	s_lshl_b32 s15, s10, 6
	v_cndmask_b32_e64 v64, v193, 0, s[0:1]
	s_or_b32 s0, s15, 63
	v_cmp_le_i32_e32 vcc, s0, v171
	s_and_saveexec_b64 s[0:1], vcc
	s_xor_b64 s[0:1], exec, s[0:1]
	s_cbranch_execz .LBB0_380
	v_lshlrev_b32_e32 v80, 1, v170
	v_add3_u32 v109, s14, v185, v80
	ds_read_b128 v[212:215], v109
	ds_read_b128 v[216:219], v109 offset:4608
	ds_read_b128 v[220:223], v109 offset:32
	ds_read_b128 v[224:227], v109 offset:4640
	ds_read_b128 v[228:231], v109 offset:64
	ds_read_b128 v[232:235], v109 offset:4672
	ds_read_b128 v[236:239], v109 offset:96
	ds_read_b128 v[240:243], v109 offset:4704
	v_mov_b32_e32 v65, v64
	v_mov_b32_e32 v66, v64
	v_mov_b32_e32 v67, v64
	v_mov_b32_e32 v68, v64
	v_mov_b32_e32 v69, v64
	v_mov_b32_e32 v70, v64
	v_mov_b32_e32 v71, v64
	v_mov_b32_e32 v72, v64
	v_mov_b32_e32 v73, v64
	v_mov_b32_e32 v74, v64
	v_mov_b32_e32 v75, v64
	v_mov_b32_e32 v76, v64
	v_mov_b32_e32 v77, v64
	v_mov_b32_e32 v78, v64
	v_mov_b32_e32 v79, v64
	s_nop 0
	s_waitcnt lgkmcnt(7)
	v_mfma_f32_32x32x16_bf16 v[80:95], v[212:215], v[130:133], v[64:79]
	s_waitcnt lgkmcnt(6)
	v_mfma_f32_32x32x16_bf16 v[64:79], v[216:219], v[130:133], v[64:79]
	s_waitcnt lgkmcnt(5)
	v_mfma_f32_32x32x16_bf16 v[80:95], v[220:223], v[134:137], v[80:95]
	s_waitcnt lgkmcnt(4)
	v_mfma_f32_32x32x16_bf16 v[64:79], v[224:227], v[134:137], v[64:79]
	s_waitcnt lgkmcnt(3)
	v_mfma_f32_32x32x16_bf16 v[80:95], v[228:231], v[138:141], v[80:95]
	s_waitcnt lgkmcnt(2)
	v_mfma_f32_32x32x16_bf16 v[64:79], v[232:235], v[138:141], v[64:79]
	s_waitcnt lgkmcnt(1)
	v_mfma_f32_32x32x16_bf16 v[80:95], v[236:239], v[142:145], v[80:95]
	s_waitcnt lgkmcnt(0)
	v_mfma_f32_32x32x16_bf16 v[64:79], v[240:243], v[142:145], v[64:79]
	v_add3_u32 v251, s14, v186, v170
	v_add_u32_e32 v255, 0x2000, v251
	v_add_u32_e32 v251, 0x3000, v251
	ds_read2_b64 v[212:215], v255 offset0:128 offset1:130
	ds_read2_b64 v[216:219], v255 offset0:132 offset1:134
	ds_read2_b64 v[220:223], v255 offset0:136 offset1:138
	ds_read2_b64 v[224:227], v251 offset0:160 offset1:162
	ds_read2_b64 v[228:231], v251 offset0:168 offset1:170
	ds_read2_b64 v[232:235], v255 offset0:140 offset1:142
	ds_read2_b64 v[236:239], v251 offset0:164 offset1:166
	ds_read2_b64 v[240:243], v251 offset0:172 offset1:174
	s_nop 9
	v_exp_f32_e32 v116, v80
	v_exp_f32_e32 v80, v82
	v_exp_f32_e32 v82, v84
	v_exp_f32_e32 v84, v86
	v_exp_f32_e32 v86, v88
	v_exp_f32_e32 v88, v89
	v_exp_f32_e32 v118, v90
	v_exp_f32_e32 v117, v64
	v_exp_f32_e32 v64, v81
	v_exp_f32_e32 v65, v65
	v_exp_f32_e32 v81, v66
	v_exp_f32_e32 v66, v83
	v_exp_f32_e32 v67, v67
	v_exp_f32_e32 v83, v68
	v_exp_f32_e32 v68, v85
	v_exp_f32_e32 v85, v70
	v_exp_f32_e32 v70, v87
	v_exp_f32_e32 v87, v72
	v_exp_f32_e32 v89, v73
	v_pk_add_f32 v[72:73], v[116:117], 0 op_sel_hi:[1,0]
	v_exp_f32_e32 v69, v69
	v_pk_add_f32 v[72:73], v[64:65], v[72:73]
	v_exp_f32_e32 v71, v71
	v_pk_add_f32 v[72:73], v[80:81], v[72:73]
	v_exp_f32_e32 v119, v74
	v_pk_add_f32 v[72:73], v[66:67], v[72:73]
	v_exp_f32_e32 v90, v91
	v_pk_add_f32 v[72:73], v[82:83], v[72:73]
	v_exp_f32_e32 v91, v75
	v_pk_add_f32 v[72:73], v[68:69], v[72:73]
	v_exp_f32_e32 v120, v92
	v_pk_add_f32 v[72:73], v[84:85], v[72:73]
	v_exp_f32_e32 v121, v76
	v_pk_add_f32 v[72:73], v[70:71], v[72:73]
	v_exp_f32_e32 v92, v93
	v_pk_add_f32 v[72:73], v[86:87], v[72:73]
	v_exp_f32_e32 v93, v77
	v_pk_add_f32 v[72:73], v[88:89], v[72:73]
	v_exp_f32_e32 v122, v94
	v_exp_f32_e32 v123, v78
	v_pk_add_f32 v[72:73], v[118:119], v[72:73]
	v_exp_f32_e32 v94, v95
	v_exp_f32_e32 v95, v79
	v_pk_add_f32 v[72:73], v[90:91], v[72:73]
	v_cvt_pk_bf16_f32 v79, v84, v70
	v_pk_add_f32 v[72:73], v[120:121], v[72:73]
	v_cvt_pk_bf16_f32 v70, v120, v92
	v_pk_add_f32 v[72:73], v[92:93], v[72:73]
	v_add3_u32 v92, s14, v186, v170
	v_pk_add_f32 v[72:73], v[122:123], v[72:73]
	v_cvt_pk_bf16_f32 v77, v80, v66
	v_pk_add_f32 v[72:73], v[94:95], v[72:73]
	v_cvt_pk_bf16_f32 v66, v121, v93
	v_add_f32_e32 v72, v72, v73
	v_add_u32_e32 v93, 0x2000, v92
	v_add_f32_e32 v175, v175, v72
	v_cvt_pk_bf16_f32 v76, v116, v64
	v_cvt_pk_bf16_f32 v72, v117, v65
	v_cvt_pk_bf16_f32 v73, v81, v67
	v_cvt_pk_bf16_f32 v78, v82, v68
	v_cvt_pk_bf16_f32 v74, v83, v69
	v_cvt_pk_bf16_f32 v75, v85, v71
	v_cvt_pk_bf16_f32 v68, v86, v88
	v_cvt_pk_bf16_f32 v64, v87, v89
	v_cvt_pk_bf16_f32 v69, v118, v90
	v_cvt_pk_bf16_f32 v65, v119, v91
	s_waitcnt lgkmcnt(0)
	v_mfma_f32_32x32x16_bf16 v[48:63], v[212:215], v[76:79], v[48:63]
	v_add_u32_e32 v92, 0x3000, v92
	v_cvt_pk_bf16_f32 v71, v122, v94
	v_cvt_pk_bf16_f32 v67, v123, v95
	v_mfma_f32_32x32x16_bf16 v[48:63], v[220:223], v[72:75], v[48:63]
	v_mfma_f32_32x32x16_bf16 v[32:47], v[224:227], v[76:79], v[32:47]
	v_mfma_f32_32x32x16_bf16 v[32:47], v[228:231], v[72:75], v[32:47]
	v_mfma_f32_32x32x16_bf16 v[48:63], v[216:219], v[68:71], v[48:63]
	v_mfma_f32_32x32x16_bf16 v[48:63], v[232:235], v[64:67], v[48:63]
	v_mfma_f32_32x32x16_bf16 v[32:47], v[236:239], v[68:71], v[32:47]
	v_mfma_f32_32x32x16_bf16 v[32:47], v[240:243], v[64:67], v[32:47]
